# SSD segment between the barriers: waves 4-7 run the state update first (role split between SIMD partners)
# speedup vs baseline: 1.0036x; 1.0036x over previous
.LBB0_347:
	s_or_b64 exec, exec, s[0:1]
	v_mul_f32_e32 v4, 0x3fb8aa3b, v4
	v_exp_f32_e32 v63, v4
	v_cmp_gt_i32_e64 s[38:39], s35, v1
	v_add_u32_e32 v4, 0xffffff00, v1
	v_mov_b32_e32 v5, 0x1000
	v_cndmask_b32_e64 v51, v4, v1, s[38:39]
	v_mov_b32_e32 v4, 0x1200
	s_lshl_b32 s0, s36, 4
	v_cndmask_b32_e64 v4, v4, v5, s[38:39]
	s_and_b32 s0, s0, 0x180
	v_ashrrev_i32_e32 v48, 4, v51
	v_or_b32_e32 v54, s0, v4
	v_lshlrev_b32_e32 v4, 3, v51
	s_movk_i32 s0, 0x78
	s_lshl_b32 s23, s36, 6
	s_lshl_b32 s85, s37, 12
	v_and_or_b32 v4, v4, s0, v54
	s_bitset1_b32 s23, 11
	v_lshlrev_b32_e32 v50, 2, v48
	s_add_i32 s70, s85, -16
	v_and_or_b32 v20, v2, 60, s23
	v_subrev_u32_e32 v5, 48, v50
	v_lshlrev_b32_e32 v2, 1, v4
	v_cmp_lt_i32_e32 vcc, 15, v48
	v_mov_b32_e32 v52, s70
	v_lshl_add_u64 v[22:23], s[96:97], 0, v[2:3]
	v_max_i32_e32 v2, 0, v5
	v_cndmask_b32_e32 v4, v229, v52, vcc
	v_add_u32_e32 v2, v2, v4
	v_mad_i64_i32 v[4:5], s[0:1], v2, s29, v[22:23]
	v_subrev_u32_e32 v2, 47, v50
	v_cmp_lt_i32_e32 vcc, 15, v2
	v_max_i32_e32 v8, 0, v2
	v_ashrrev_i32_e32 v49, 4, v1
	v_cndmask_b32_e32 v2, v229, v52, vcc
	v_add_u32_e32 v2, v2, v8
	v_mad_i64_i32 v[8:9], s[26:27], v2, s29, v[22:23]
	v_subrev_u32_e32 v2, 46, v50
	v_cmp_lt_i32_e32 vcc, 15, v2
	v_max_i32_e32 v12, 0, v2
	v_lshlrev_b32_e32 v55, 1, v49
	v_cndmask_b32_e32 v2, v229, v52, vcc
	v_add_u32_e32 v2, v2, v12
	v_mad_i64_i32 v[12:13], s[26:27], v2, s29, v[22:23]
	v_subrev_u32_e32 v2, 45, v50
	v_cmp_lt_i32_e32 vcc, 15, v2
	v_max_i32_e32 v16, 0, v2
	v_subrev_u32_e32 v21, 48, v55
	v_cndmask_b32_e32 v2, v229, v52, vcc
	v_add_u32_e32 v2, v2, v16
	v_mad_i64_i32 v[16:17], s[26:27], v2, s29, v[22:23]
	v_lshlrev_b32_e32 v2, 1, v20
	v_cmp_lt_i32_e32 vcc, 31, v49
	v_lshl_add_u64 v[46:47], s[96:97], 0, v[2:3]
	v_max_i32_e32 v2, 0, v21
	v_cndmask_b32_e32 v20, v229, v52, vcc
	v_add_u32_e32 v2, v2, v20
	v_mad_i64_i32 v[20:21], s[26:27], v2, s29, v[46:47]
	v_subrev_u32_e32 v2, 47, v55
	v_cmp_lt_i32_e32 vcc, 15, v2
	global_load_dwordx2 v[40:41], v[20:21], off
	v_max_i32_e32 v20, 0, v2
	v_cndmask_b32_e32 v2, v229, v52, vcc
	v_and_b32_e32 v65, 63, v1
	v_add_u32_e32 v2, v2, v20
	v_mad_i64_i32 v[20:21], s[26:27], v2, s29, v[46:47]
	v_max_u32_e32 v2, 48, v65
	v_readlane_b32 s42, v252, 52
	v_lshlrev_b32_e32 v2, 7, v2
	v_readlane_b32 s43, v252, 53
	global_load_dwordx2 v[42:43], v[20:21], off
	s_mov_b32 s24, 0x3fe000
	v_lshl_add_u64 v[20:21], s[42:43], 0, v[2:3]
	v_lshl_add_u64 v[20:21], v[20:21], 0, s[72:73]
	v_add_co_u32_e32 v20, vcc, s24, v20
	v_add_u32_e32 v2, 16, v50
	s_nop 0
	v_addc_co_u32_e32 v21, vcc, 0, v21, vcc
	v_cmp_lt_i32_e32 vcc, -1, v48
	global_load_dword v20, v[20:21], off offset:2048
	v_max_i32_e32 v2, 0, v2
	v_cndmask_b32_e32 v21, v229, v52, vcc
	v_add_u32_e32 v2, v2, v21
	v_mad_i64_i32 v[24:25], s[26:27], v2, s29, v[22:23]
	v_add_u32_e32 v2, 17, v50
	v_cmp_lt_i32_e32 vcc, 15, v2
	v_max_i32_e32 v21, 0, v2
	global_load_dwordx4 v[24:27], v[24:25], off
	v_cndmask_b32_e32 v2, v229, v52, vcc
	v_add_u32_e32 v2, v2, v21
	v_mad_i64_i32 v[28:29], s[26:27], v2, s29, v[22:23]
	v_add_u32_e32 v2, 18, v50
	v_cmp_lt_i32_e32 vcc, 15, v2
	v_max_i32_e32 v21, 0, v2
	s_ashr_i32 s21, s25, 8
	v_cndmask_b32_e32 v2, v229, v52, vcc
	v_add_u32_e32 v2, v2, v21
	v_mad_i64_i32 v[32:33], s[26:27], v2, s29, v[22:23]
	v_add_u32_e32 v2, 19, v50
	v_cmp_lt_i32_e32 vcc, 15, v2
	v_max_i32_e32 v21, 0, v2
	global_load_dwordx4 v[28:31], v[28:29], off
	v_cndmask_b32_e32 v2, v229, v52, vcc
	v_add_u32_e32 v2, v2, v21
	v_mad_i64_i32 v[22:23], s[26:27], v2, s29, v[22:23]
	v_add_u32_e32 v2, 16, v55
	v_cmp_lt_i32_e32 vcc, -1, v49
	v_max_i32_e32 v2, 0, v2
	global_load_dwordx4 v[36:39], v[22:23], off
	v_cndmask_b32_e32 v21, v229, v52, vcc
	v_add_u32_e32 v2, v2, v21
	v_mad_i64_i32 v[22:23], s[26:27], v2, s29, v[46:47]
	v_add_u32_e32 v2, 17, v55
	v_cmp_lt_i32_e32 vcc, 15, v2
	v_max_i32_e32 v21, 0, v2
	global_load_dwordx2 v[44:45], v[22:23], off
	v_cndmask_b32_e32 v2, v229, v52, vcc
	v_add_u32_e32 v2, v2, v21
	v_mad_i64_i32 v[22:23], s[26:27], v2, s29, v[46:47]
	v_or_b32_e32 v56, s85, v65
	s_lshr_b32 s22, s25, 6
	s_bfe_u32 s20, s25, 0x20006
	v_ashrrev_i32_e32 v57, 31, v56
	s_lshl_b32 s24, s21, 5
	s_sub_i32 s37, s85, 64
	s_lshl_b32 s26, s36, 7
	global_load_dwordx4 v[32:35], v[32:33], off
	s_add_u32 s36, s96, s26
	global_load_dwordx2 v[46:47], v[22:23], off
	v_lshlrev_b64 v[22:23], 7, v[56:57]
	v_and_b32_e32 v94, 15, v1
	v_lshl_add_u64 v[22:23], s[42:43], 0, v[22:23]
	s_addc_u32 s42, s97, 0
	s_lshl_b32 s27, s20, 4
	s_lshl_b32 s26, s20, 5
	v_or_b32_e32 v86, s24, v94
	s_add_u32 s74, s36, s26
	v_lshrrev_b32_e32 v2, 1, v1
	v_lshl_add_u64 v[22:23], v[22:23], 0, s[72:73]
	s_addc_u32 s75, s42, 0
	v_and_b32_e32 v2, 24, v2
	v_cmp_lt_i32_e32 vcc, 63, v86
	v_mov_b32_e32 v21, s37
	global_load_dword v57, v[22:23], off
	v_lshl_add_u64 v[22:23], s[74:75], 0, v[2:3]
	v_max_i32_e32 v2, 48, v86
	v_cndmask_b32_e32 v52, v230, v21, vcc
	v_or_b32_e32 v87, 16, v86
	v_add_u32_e32 v2, v52, v2
	v_cmp_lt_i32_e32 vcc, 63, v87
	v_mad_i64_i32 v[52:53], s[36:37], v2, s29, v[22:23]
	v_max_i32_e32 v2, 48, v87
	v_cndmask_b32_e32 v21, v230, v21, vcc
	v_add_u32_e32 v2, v21, v2
	v_mad_i64_i32 v[22:23], s[36:37], v2, s29, v[22:23]
	global_load_dwordx4 v[4:7], v[4:5], off
	s_cmp_lt_u32 s25, 64
	global_load_dwordx4 v[8:11], v[8:9], off
	s_cselect_b64 s[60:61], -1, 0
	s_sub_u32 s98, s25, 0x100
	s_cmp_lt_u32 s98, 64
	s_cselect_b64 s[98:99], -1, 0
	s_cmp_lt_u32 s25, 0x100
	s_cselect_b32 s99, 0, -1
	s_mov_b32 s100, 0x3fb8aa3b
	s_mov_b32 s101, 0x3fb8aa3b
	global_load_dwordx4 v[12:15], v[12:13], off
	v_cmp_lt_i32_e64 s[0:1], 11, v48
	global_load_dwordx4 v[16:19], v[16:17], off
	v_cmp_lt_i32_e64 s[40:41], 23, v49
	global_load_dwordx2 v[52:53], v[52:53], off
	s_and_b64 vcc, exec, s[60:61]
	global_load_dwordx2 v[84:85], v[22:23], off
	s_waitcnt lgkmcnt(0)
	s_barrier
	s_cbranch_vccz .LBB0_349
	v_cmp_lt_u32_e32 vcc, 47, v65
	v_mov_b32_e32 v21, v3
	s_waitcnt vmcnt(13)
	v_cndmask_b32_e32 v2, 0, v20, vcc
	v_mul_f32_e64 v20, v2, -v63
	s_nop 1
	v_mov_b32_dpp v21, v20 row_shr:1 row_mask:0xf bank_mask:0xf
	v_fma_f32 v20, v2, -v63, v21
	v_mov_b32_e32 v21, v3
	s_nop 0
	v_add_f32_dpp v20, v20, v20 row_shr:2 row_mask:0xf bank_mask:0xf bound_ctrl:1
	s_nop 1
	v_add_f32_dpp v20, v20, v20 row_shr:4 row_mask:0xf bank_mask:0xf bound_ctrl:1
	s_nop 1
	v_add_f32_dpp v20, v20, v20 row_shr:8 row_mask:0xf bank_mask:0xf bound_ctrl:1
	s_nop 1
	v_mov_b32_dpp v21, v20 row_bcast:15 row_mask:0xa bank_mask:0xf
	v_add_f32_e32 v20, v20, v21
	v_mov_b32_e32 v21, v3
	s_nop 1
	v_mov_b32_dpp v21, v20 row_bcast:31 row_mask:0xc bank_mask:0xf
	v_add_f32_e32 v20, v20, v21
	v_lshl_add_u32 v21, v65, 2, 0
	v_add_u32_e32 v22, 0x1a400, v21
	ds_write_b32 v22, v2
	v_add_u32_e32 v2, 0x1a600, v21
	ds_write_b32 v2, v20

.Lscan1_skip:
	v_mov_b32_e32 v54, s87
	v_add_u32_e32 v55, v71, v96
	ds_read_b32 v54, v54
	s_waitcnt vmcnt(7)
	ds_write_b64 v55, v[58:59]
	v_add_u32_e32 v55, v71, v97
	s_waitcnt vmcnt(6)
	ds_write_b64 v55, v[60:61]
	ds_read_b64 v[88:89], v99
	ds_read_b64 v[160:161], v98
	v_lshlrev_b32_e32 v157, 16, v60
	v_lshlrev_b32_e32 v156, 16, v58
	s_mul_hi_i32 s1, s21, 0x3400
	s_waitcnt lgkmcnt(1)
	v_sub_f32_e32 v55, v54, v88
	v_mul_f32_e32 v55, 0x3fb8aa3b, v55
	v_exp_f32_e32 v88, v55
	v_sub_f32_e32 v55, v54, v89
	v_mul_f32_e32 v55, 0x3fb8aa3b, v55
	v_exp_f32_e32 v89, v55
	s_waitcnt lgkmcnt(0)
	v_pk_mul_f32 v[162:163], v[160:161], v[156:157]
	s_mulk_i32 s21, 0x3400
	v_cvt_pk_bf16_f32 v55, v162, v163
	v_pk_mul_f32 v[88:89], v[160:161], v[88:89]
	s_add_u32 s0, s96, s21
	v_pk_mul_f32 v[156:157], v[88:89], v[156:157]
	s_addc_u32 s1, s97, s1
	v_cvt_pk_bf16_f32 v153, v156, v157
	v_and_b32_e32 v157, 0xffff0000, v60
	v_and_b32_e32 v156, 0xffff0000, v58
	v_pk_mul_f32 v[162:163], v[160:161], v[156:157]
	v_pk_mul_f32 v[156:157], v[88:89], v[156:157]
	v_cvt_pk_bf16_f32 v58, v162, v163
	ds_write2_b32 v126, v55, v58 offset1:36
	v_cvt_pk_bf16_f32 v55, v156, v157
	v_lshlrev_b32_e32 v157, 16, v61
	v_lshlrev_b32_e32 v156, 16, v59
	v_and_b32_e32 v61, 0xffff0000, v61
	v_and_b32_e32 v60, 0xffff0000, v59
	v_pk_mul_f32 v[162:163], v[160:161], v[156:157]
	v_pk_mul_f32 v[58:59], v[160:161], v[60:61]
	ds_write2_b32 v137, v153, v55 offset1:36
	v_cvt_pk_bf16_f32 v55, v162, v163
	v_cvt_pk_bf16_f32 v58, v58, v59
	v_lshlrev_b32_e32 v2, 1, v62
	v_pk_mul_f32 v[156:157], v[88:89], v[156:157]
	ds_write2_b32 v126, v55, v58 offset0:72 offset1:108
	v_pk_mul_f32 v[58:59], v[88:89], v[60:61]
	v_lshlrev_b32_e32 v88, 1, v64
	v_mov_b32_e32 v89, v3
	v_lshl_add_u64 v[20:21], s[0:1], 0, v[2:3]
	v_lshl_add_u64 v[60:61], s[0:1], 0, v[88:89]
	v_lshl_add_u64 v[4:5], v[72:73], 1, v[20:21]
	v_lshl_add_u64 v[8:9], v[74:75], 1, v[20:21]
	v_lshl_add_u64 v[12:13], v[76:77], 1, v[20:21]
	v_lshl_add_u64 v[20:21], v[78:79], 1, v[20:21]
	v_cvt_pk_bf16_f32 v55, v58, v59
	v_lshl_add_u64 v[58:59], v[80:81], 1, v[60:61]
	v_lshl_add_u64 v[60:61], v[82:83], 1, v[60:61]
	global_load_dwordx4 v[4:7], v[4:5], off
	s_cmp_lg_u32 s36, 0
	global_load_dwordx4 v[8:11], v[8:9], off
	v_cvt_pk_bf16_f32 v153, v156, v157
	global_load_dwordx4 v[12:15], v[12:13], off
	s_cselect_b64 s[0:1], -1, 0
	global_load_dwordx4 v[20:23], v[20:21], off
	s_max_u32 s21, s20, 1
	global_load_dwordx2 v[58:59], v[58:59], off
	ds_write2_b32 v137, v153, v55 offset0:72 offset1:108
	global_load_dwordx2 v[60:61], v[60:61], off
	v_lshl_add_u32 v55, s21, 6, v103
	v_cmp_lt_i32_e32 vcc, -1, v55
	s_waitcnt lgkmcnt(0)
	s_barrier
	s_cmp_eq_u64 s[82:83], 0
	s_cbranch_scc1 .Lssq1_own
	v_lshlrev_b32_e32 v201, 2, v232
	global_store_dword v201, v3, s[66:67]
	s_cmp_eq_u32 s99, 0
	s_cbranch_scc1 .LBB0_360
	v_mul_f32_e32 v54, 0x3fb8aa3b, v54
	v_exp_f32_e32 v54, v54
	ds_read_b128 v[176:179], v139
	ds_read_b64_tr_b16 v[180:181], v140
	ds_read_b64_tr_b16 v[182:183], v140 offset:1088
	ds_read_b64_tr_b16 v[184:185], v140 offset:32
	ds_read_b64_tr_b16 v[186:187], v140 offset:1120
	ds_read_b64_tr_b16 v[188:189], v140 offset:64
	ds_read_b64_tr_b16 v[190:191], v140 offset:1152
	ds_read_b64_tr_b16 v[192:193], v140 offset:96
	ds_read_b64_tr_b16 v[194:195], v140 offset:1184
	v_add_u32_e32 v159, v108, v111
	ds_read_b128 v[172:175], v159
	ds_read_b64_tr_b16 v[160:161], v140 offset:8704
	ds_read_b64_tr_b16 v[162:163], v140 offset:9792
	ds_read_b64_tr_b16 v[164:165], v140 offset:8736
	ds_read_b64_tr_b16 v[166:167], v140 offset:9824
	v_pk_mul_f32 v[50:51], v[50:51], v[54:55] op_sel_hi:[1,0]
	v_pk_mul_f32 v[48:49], v[48:49], v[54:55] op_sel_hi:[1,0]
	v_pk_mul_f32 v[42:43], v[42:43], v[54:55] op_sel_hi:[1,0]
	v_pk_mul_f32 v[40:41], v[40:41], v[54:55] op_sel_hi:[1,0]
	v_pk_mul_f32 v[46:47], v[46:47], v[54:55] op_sel_hi:[1,0]
	v_pk_mul_f32 v[44:45], v[44:45], v[54:55] op_sel_hi:[1,0]
	v_pk_mul_f32 v[38:39], v[38:39], v[54:55] op_sel_hi:[1,0]
	v_pk_mul_f32 v[36:37], v[36:37], v[54:55] op_sel_hi:[1,0]
	s_waitcnt lgkmcnt(5)
	v_mfma_f32_16x16x32_bf16 v[48:51], v[180:183], v[176:179], v[48:51]
	v_mfma_f32_16x16x32_bf16 v[40:43], v[184:187], v[176:179], v[40:43]
	v_mfma_f32_16x16x32_bf16 v[44:47], v[188:191], v[176:179], v[44:47]
	v_mfma_f32_16x16x32_bf16 v[36:39], v[192:195], v[176:179], v[36:39]
	ds_read_b64_tr_b16 v[168:169], v140 offset:8768
	ds_read_b64_tr_b16 v[170:171], v140 offset:9856
	ds_read_b64_tr_b16 v[202:203], v140 offset:8800
	ds_read_b64_tr_b16 v[204:205], v140 offset:9888
	s_waitcnt lgkmcnt(4)
	v_mfma_f32_16x16x32_bf16 v[48:51], v[160:163], v[172:175], v[48:51]
	v_mfma_f32_16x16x32_bf16 v[40:43], v[164:167], v[172:175], v[40:43]
	s_waitcnt lgkmcnt(0)
	v_mfma_f32_16x16x32_bf16 v[44:47], v[168:171], v[172:175], v[44:47]
	v_mfma_f32_16x16x32_bf16 v[36:39], v[202:205], v[172:175], v[36:39]
	v_add_u32_e32 v156, v106, v107
	ds_read_b128 v[160:163], v156 offset:34816
	ds_read_b128 v[164:167], v156 offset:34880
	ds_read_b128 v[168:171], v156 offset:17408
	ds_read_b128 v[172:175], v156 offset:17472
	ds_read_b128 v[176:179], v138
	ds_read_b128 v[180:183], v138 offset:64
	ds_read_b128 v[184:187], v138 offset:4352
	ds_read_b128 v[188:191], v138 offset:4416
	ds_read_b128 v[192:195], v156 offset:34944
	ds_read_b128 v[202:205], v156 offset:35008
	ds_read_b128 v[206:209], v156 offset:17536
	ds_read_b128 v[210:213], v156 offset:17600
	ds_read_b128 v[214:217], v138 offset:128
	ds_read_b128 v[236:239], v138 offset:192
	ds_read_b128 v[240:243], v138 offset:4480
	ds_read_b128 v[244:247], v138 offset:4544
	s_waitcnt lgkmcnt(11)
	v_mfma_f32_16x16x32_bf16 v[248:251], v[160:163], v[176:179], 0
	v_mfma_f32_16x16x32_bf16 v[176:179], v[168:171], v[176:179], 0
	s_waitcnt lgkmcnt(9)
	v_mfma_f32_16x16x32_bf16 v[160:163], v[160:163], v[184:187], 0
	v_mfma_f32_16x16x32_bf16 v[168:171], v[168:171], v[184:187], 0
	v_mfma_f32_16x16x32_bf16 v[184:187], v[164:167], v[180:183], v[248:251]
	v_mfma_f32_16x16x32_bf16 v[176:179], v[172:175], v[180:183], v[176:179]
	s_waitcnt lgkmcnt(8)
	v_mfma_f32_16x16x32_bf16 v[160:163], v[164:167], v[188:191], v[160:163]
	v_mfma_f32_16x16x32_bf16 v[164:167], v[172:175], v[188:191], v[168:171]
	s_waitcnt lgkmcnt(3)
	v_mfma_f32_16x16x32_bf16 v[168:171], v[192:195], v[214:217], v[184:187]
	v_mfma_f32_16x16x32_bf16 v[172:175], v[206:209], v[214:217], v[176:179]
	s_waitcnt lgkmcnt(1)
	v_mfma_f32_16x16x32_bf16 v[160:163], v[192:195], v[240:243], v[160:163]
	s_nop 0
	v_mfma_f32_16x16x32_bf16 v[164:167], v[206:209], v[240:243], v[164:167]
	s_waitcnt lgkmcnt(0)
	v_mfma_f32_16x16x32_bf16 v[160:163], v[202:205], v[244:247], v[160:163]
	v_mfma_f32_16x16x32_bf16 v[168:171], v[202:205], v[236:239], v[168:171]
	v_mfma_f32_16x16x32_bf16 v[172:175], v[210:213], v[236:239], v[172:175]
	v_mfma_f32_16x16x32_bf16 v[164:167], v[210:213], v[244:247], v[164:167]
	ds_read_b32 v55, v109
	ds_read_b128 v[202:205], v127
	s_waitcnt lgkmcnt(0)
	v_pk_add_f32 v[198:199], v[54:55], v[202:203] op_sel:[1,0] op_sel_hi:[1,1] neg_lo:[0,1] neg_hi:[0,1]
	v_pk_add_f32 v[222:223], v[54:55], v[204:205] op_sel:[1,0] op_sel_hi:[1,1] neg_lo:[0,1] neg_hi:[0,1]
	v_pk_mul_f32 v[198:199], v[198:199], s[100:101]
	v_pk_mul_f32 v[222:223], v[222:223], s[100:101]
	v_exp_f32_e32 v198, v198
	v_exp_f32_e32 v199, v199
	v_exp_f32_e32 v222, v222
	v_exp_f32_e32 v223, v223
	v_pk_mul_f32 v[198:199], v[172:173], v[198:199]
	v_pk_mul_f32 v[222:223], v[174:175], v[222:223]
	v_cndmask_b32_e64 v198, v198, 0, s[42:43]
	v_cndmask_b32_e64 v199, 0, v199, s[44:45]
	v_cndmask_b32_e64 v222, v222, 0, s[46:47]
	v_cndmask_b32_e64 v223, v223, 0, s[48:49]
	v_cvt_pk_bf16_f32 v172, v198, v199
	v_cvt_pk_bf16_f32 v173, v222, v223
	ds_write_b64 v144, v[172:173]
	ds_read_b32 v89, v110
	ds_read_b128 v[172:175], v127
	v_mul_f32_e32 v55, 0x3fb8aa3b, v55
	v_exp_f32_e32 v154, v55
	s_waitcnt lgkmcnt(0)
	v_mul_f32_e32 v55, 0x3fb8aa3b, v89
	v_pk_add_f32 v[198:199], v[88:89], v[172:173] op_sel:[1,0] op_sel_hi:[1,1] neg_lo:[0,1] neg_hi:[0,1]
	v_pk_add_f32 v[222:223], v[88:89], v[174:175] op_sel:[1,0] op_sel_hi:[1,1] neg_lo:[0,1] neg_hi:[0,1]
	v_pk_mul_f32 v[198:199], v[198:199], s[100:101]
	v_pk_mul_f32 v[222:223], v[222:223], s[100:101]
	v_exp_f32_e32 v198, v198
	v_exp_f32_e32 v199, v199
	v_exp_f32_e32 v222, v222
	v_exp_f32_e32 v223, v223
	v_exp_f32_e32 v206, v55
	v_pk_mul_f32 v[198:199], v[164:165], v[198:199]
	v_pk_mul_f32 v[222:223], v[166:167], v[222:223]
	v_cndmask_b32_e64 v198, v198, 0, s[50:51]
	v_cndmask_b32_e64 v199, 0, v199, s[52:53]
	v_cndmask_b32_e64 v222, v222, 0, s[54:55]
	v_cndmask_b32_e64 v223, v223, 0, s[56:57]
	v_cvt_pk_bf16_f32 v164, v198, v199
	v_cvt_pk_bf16_f32 v165, v222, v223
	ds_write_b64 v145, v[164:165]
	v_add_u32_e32 v54, v112, v113
	s_waitcnt lgkmcnt(0)
	s_barrier
	ds_read_b128 v[176:179], v54
	ds_read_b128 v[184:187], v150
	v_add_u32_e32 v54, v112, v111
	ds_read_b128 v[164:167], v150 offset:2304
	ds_read_b128 v[188:191], v150 offset:64
	ds_read_b128 v[192:195], v54
	ds_read_b128 v[202:205], v150 offset:2368
	s_branch .LsegB1_join

.LBB0_360:
	v_add_u32_e32 v156, v106, v107
	ds_read_b128 v[160:163], v156 offset:34816
	ds_read_b128 v[164:167], v156 offset:34880
	ds_read_b128 v[168:171], v156 offset:17408
	ds_read_b128 v[172:175], v156 offset:17472
	ds_read_b128 v[176:179], v138
	ds_read_b128 v[180:183], v138 offset:64
	ds_read_b128 v[184:187], v138 offset:4352
	ds_read_b128 v[188:191], v138 offset:4416
	ds_read_b128 v[192:195], v156 offset:34944
	ds_read_b128 v[202:205], v156 offset:35008
	ds_read_b128 v[206:209], v156 offset:17536
	ds_read_b128 v[210:213], v156 offset:17600
	ds_read_b128 v[214:217], v138 offset:128
	ds_read_b128 v[236:239], v138 offset:192
	ds_read_b128 v[240:243], v138 offset:4480
	ds_read_b128 v[244:247], v138 offset:4544
	s_waitcnt lgkmcnt(11)
	v_mfma_f32_16x16x32_bf16 v[248:251], v[160:163], v[176:179], 0
	v_mfma_f32_16x16x32_bf16 v[176:179], v[168:171], v[176:179], 0
	s_waitcnt lgkmcnt(9)
	v_mfma_f32_16x16x32_bf16 v[160:163], v[160:163], v[184:187], 0
	v_mfma_f32_16x16x32_bf16 v[168:171], v[168:171], v[184:187], 0
	v_mfma_f32_16x16x32_bf16 v[184:187], v[164:167], v[180:183], v[248:251]
	v_mfma_f32_16x16x32_bf16 v[176:179], v[172:175], v[180:183], v[176:179]
	s_waitcnt lgkmcnt(8)
	v_mfma_f32_16x16x32_bf16 v[160:163], v[164:167], v[188:191], v[160:163]
	v_mfma_f32_16x16x32_bf16 v[164:167], v[172:175], v[188:191], v[168:171]
	s_waitcnt lgkmcnt(3)
	v_mfma_f32_16x16x32_bf16 v[168:171], v[192:195], v[214:217], v[184:187]
	v_mfma_f32_16x16x32_bf16 v[172:175], v[206:209], v[214:217], v[176:179]
	s_waitcnt lgkmcnt(1)
	v_mfma_f32_16x16x32_bf16 v[160:163], v[192:195], v[240:243], v[160:163]
	s_nop 0
	ds_read_b128 v[176:179], v139
	ds_read_b64_tr_b16 v[180:181], v140
	ds_read_b64_tr_b16 v[182:183], v140 offset:1088
	ds_read_b64_tr_b16 v[184:185], v140 offset:32
	ds_read_b64_tr_b16 v[186:187], v140 offset:1120
	ds_read_b64_tr_b16 v[188:189], v140 offset:64
	ds_read_b64_tr_b16 v[190:191], v140 offset:1152
	ds_read_b64_tr_b16 v[192:193], v140 offset:96
	ds_read_b64_tr_b16 v[194:195], v140 offset:1184
	v_mfma_f32_16x16x32_bf16 v[164:167], v[206:209], v[240:243], v[164:167]
	s_waitcnt lgkmcnt(9)
	v_mfma_f32_16x16x32_bf16 v[160:163], v[202:205], v[244:247], v[160:163]
	v_mfma_f32_16x16x32_bf16 v[168:171], v[202:205], v[236:239], v[168:171]
	v_mfma_f32_16x16x32_bf16 v[172:175], v[210:213], v[236:239], v[172:175]
	v_mfma_f32_16x16x32_bf16 v[164:167], v[210:213], v[244:247], v[164:167]
	ds_read_b32 v55, v109
	ds_read_b128 v[202:205], v127
	s_waitcnt lgkmcnt(0)
	v_pk_add_f32 v[198:199], v[54:55], v[202:203] op_sel:[1,0] op_sel_hi:[1,1] neg_lo:[0,1] neg_hi:[0,1]
	v_pk_add_f32 v[222:223], v[54:55], v[204:205] op_sel:[1,0] op_sel_hi:[1,1] neg_lo:[0,1] neg_hi:[0,1]
	v_pk_mul_f32 v[198:199], v[198:199], s[100:101]
	v_pk_mul_f32 v[222:223], v[222:223], s[100:101]
	v_exp_f32_e32 v198, v198
	v_exp_f32_e32 v199, v199
	v_exp_f32_e32 v222, v222
	v_exp_f32_e32 v223, v223
	v_pk_mul_f32 v[198:199], v[172:173], v[198:199]
	v_pk_mul_f32 v[222:223], v[174:175], v[222:223]
	v_cndmask_b32_e64 v198, v198, 0, s[42:43]
	v_cndmask_b32_e64 v199, 0, v199, s[44:45]
	v_cndmask_b32_e64 v222, v222, 0, s[46:47]
	v_cndmask_b32_e64 v223, v223, 0, s[48:49]
	v_cvt_pk_bf16_f32 v172, v198, v199
	v_cvt_pk_bf16_f32 v173, v222, v223
	ds_write_b64 v144, v[172:173]
	ds_read_b32 v89, v110
	ds_read_b128 v[172:175], v127
	v_mul_f32_e32 v55, 0x3fb8aa3b, v55
	v_exp_f32_e32 v154, v55
	s_waitcnt lgkmcnt(0)
	v_mul_f32_e32 v55, 0x3fb8aa3b, v89
	v_pk_add_f32 v[198:199], v[88:89], v[172:173] op_sel:[1,0] op_sel_hi:[1,1] neg_lo:[0,1] neg_hi:[0,1]
	v_pk_add_f32 v[222:223], v[88:89], v[174:175] op_sel:[1,0] op_sel_hi:[1,1] neg_lo:[0,1] neg_hi:[0,1]
	v_pk_mul_f32 v[198:199], v[198:199], s[100:101]
	v_pk_mul_f32 v[222:223], v[222:223], s[100:101]
	v_exp_f32_e32 v198, v198
	v_exp_f32_e32 v199, v199
	v_exp_f32_e32 v222, v222
	v_exp_f32_e32 v223, v223
	v_exp_f32_e32 v206, v55
	v_pk_mul_f32 v[198:199], v[164:165], v[198:199]
	v_pk_mul_f32 v[222:223], v[166:167], v[222:223]
	v_cndmask_b32_e64 v198, v198, 0, s[50:51]
	v_cndmask_b32_e64 v199, 0, v199, s[52:53]
	v_cndmask_b32_e64 v222, v222, 0, s[54:55]
	v_cndmask_b32_e64 v223, v223, 0, s[56:57]
	v_cvt_pk_bf16_f32 v164, v198, v199
	v_cvt_pk_bf16_f32 v165, v222, v223
	ds_write_b64 v145, v[164:165]
	v_mul_f32_e32 v54, 0x3fb8aa3b, v54
	v_exp_f32_e32 v54, v54
	ds_read_b64_tr_b16 v[164:165], v140 offset:8704
	ds_read_b64_tr_b16 v[166:167], v140 offset:9792
	v_add_u32_e32 v159, v108, v111
	ds_read_b128 v[172:175], v159
	v_pk_mul_f32 v[50:51], v[50:51], v[54:55] op_sel_hi:[1,0]
	v_pk_mul_f32 v[48:49], v[48:49], v[54:55] op_sel_hi:[1,0]
	v_pk_mul_f32 v[42:43], v[42:43], v[54:55] op_sel_hi:[1,0]
	v_pk_mul_f32 v[40:41], v[40:41], v[54:55] op_sel_hi:[1,0]
	v_pk_mul_f32 v[46:47], v[46:47], v[54:55] op_sel_hi:[1,0]
	v_pk_mul_f32 v[44:45], v[44:45], v[54:55] op_sel_hi:[1,0]
	v_pk_mul_f32 v[38:39], v[38:39], v[54:55] op_sel_hi:[1,0]
	v_pk_mul_f32 v[36:37], v[36:37], v[54:55] op_sel_hi:[1,0]
	v_mfma_f32_16x16x32_bf16 v[48:51], v[180:183], v[176:179], v[48:51]
	v_add_u32_e32 v54, v112, v113
	v_mfma_f32_16x16x32_bf16 v[40:43], v[184:187], v[176:179], v[40:43]
	v_mfma_f32_16x16x32_bf16 v[44:47], v[188:191], v[176:179], v[44:47]
	v_mfma_f32_16x16x32_bf16 v[36:39], v[192:195], v[176:179], v[36:39]
	ds_read_b64_tr_b16 v[176:177], v140 offset:8736
	ds_read_b64_tr_b16 v[178:179], v140 offset:9824
	s_waitcnt lgkmcnt(2)
	v_mfma_f32_16x16x32_bf16 v[48:51], v[164:167], v[172:175], v[48:51]
	ds_read_b64_tr_b16 v[164:165], v140 offset:8768
	ds_read_b64_tr_b16 v[166:167], v140 offset:9856
	ds_read_b64_tr_b16 v[180:181], v140 offset:8800
	ds_read_b64_tr_b16 v[182:183], v140 offset:9888
	s_waitcnt lgkmcnt(0)
	s_barrier
	s_waitcnt lgkmcnt(2)
	v_mfma_f32_16x16x32_bf16 v[40:43], v[176:179], v[172:175], v[40:43]
	ds_read_b128 v[176:179], v54
	ds_read_b128 v[184:187], v150
	v_add_u32_e32 v54, v112, v111
	s_waitcnt lgkmcnt(3)
	v_mfma_f32_16x16x32_bf16 v[44:47], v[164:167], v[172:175], v[44:47]
	ds_read_b128 v[164:167], v150 offset:2304
	ds_read_b128 v[188:191], v150 offset:64
	ds_read_b128 v[192:195], v54
	ds_read_b128 v[202:205], v150 offset:2368
	s_waitcnt lgkmcnt(6)
	v_mfma_f32_16x16x32_bf16 v[36:39], v[180:183], v[172:175], v[36:39]
.LsegB1_join:
	v_mul_f32_e64 v170, v170, v154
	v_mul_f32_e64 v171, v171, v154
	v_pk_mul_f32 v[168:169], v[168:169], v[154:155] op_sel_hi:[1,0]
	v_pk_mul_f32 v[162:163], v[162:163], v[206:207] op_sel_hi:[1,0]
	v_pk_mul_f32 v[160:161], v[160:161], v[206:207] op_sel_hi:[1,0]
	s_waitcnt lgkmcnt(4)
	v_mfma_f32_16x16x32_bf16 v[168:171], v[176:179], v[184:187], v[168:171]
	v_cvt_pk_bf16_f32 v54, v48, v49
	v_cvt_pk_bf16_f32 v55, v50, v51
	v_cvt_pk_bf16_f32 v172, v40, v41
	v_cvt_pk_bf16_f32 v173, v42, v43
	v_add_u32_e32 v157, 0x8800, v151
	s_waitcnt lgkmcnt(3)
	v_mfma_f32_16x16x32_bf16 v[160:163], v[176:179], v[164:167], v[160:163]
	ds_write2_b64 v157, v[54:55], v[172:173] offset1:4
	v_cvt_pk_bf16_f32 v54, v44, v45
	v_cvt_pk_bf16_f32 v55, v46, v47
	s_waitcnt lgkmcnt(2)
	v_mfma_f32_16x16x32_bf16 v[164:167], v[192:195], v[188:191], v[168:171]
	v_cmp_lt_i32_e32 vcc, v225, v220
	v_lshl_add_u64 v[92:93], v[86:87], 0, v[92:93]
	s_nop 0
	v_cvt_pk_bf16_f32 v168, v36, v37
	v_cvt_pk_bf16_f32 v169, v38, v39
	ds_write2_b64 v157, v[54:55], v[168:169] offset0:8 offset1:12
	v_cndmask_b32_e32 v54, v218, v225, vcc
	v_lshlrev_b32_e32 v153, 2, v54
	s_waitcnt vmcnt(9)
	v_lshlrev_b32_e32 v54, 16, v52
	v_and_b32_e32 v55, 0xffff0000, v52
	v_mul_f32_e32 v52, 0xbfb8aa3b, v54
	v_exp_f32_e32 v52, v52
	v_mul_f32_e32 v89, 0xbfb8aa3b, v55
	v_exp_f32_e32 v89, v89
	ds_read_b64 v[168:169], v128
	v_add_f32_e32 v52, 1.0, v52
	v_rcp_f32_e32 v170, v52
	v_add_f32_e32 v52, 1.0, v89
	v_rcp_f32_e32 v171, v52
	s_waitcnt lgkmcnt(0)
	v_lshlrev_b32_e32 v172, 16, v168
	v_and_b32_e32 v173, 0xffff0000, v168
	v_pk_fma_f32 v[164:165], v[0:1], v[172:173], v[164:165]
	v_pk_mul_f32 v[54:55], v[170:171], v[54:55]
	v_lshlrev_b32_e32 v52, 16, v53
	v_pk_mul_f32 v[164:165], v[54:55], v[164:165]
	v_and_b32_e32 v53, 0xffff0000, v53
	v_mul_f32_e32 v54, 0xbfb8aa3b, v52
	v_exp_f32_e32 v89, v54
	v_mul_f32_e32 v54, 0xbfb8aa3b, v53
	v_exp_f32_e32 v154, v54
	v_lshlrev_b32_e32 v168, 16, v169
	v_add_f32_e32 v89, 1.0, v89
	v_rcp_f32_e32 v170, v89
	v_add_f32_e32 v89, 1.0, v154
	v_rcp_f32_e32 v171, v89
	v_and_b32_e32 v169, 0xffff0000, v169
	v_pk_fma_f32 v[166:167], v[0:1], v[168:169], v[166:167]
	v_pk_mul_f32 v[54:55], v[164:165], v[164:165]
	v_pk_mul_f32 v[52:53], v[170:171], v[52:53]
	v_add_f32_e32 v54, v54, v55
	v_pk_mul_f32 v[166:167], v[52:53], v[166:167]
	v_cmp_lt_i32_e32 vcc, v226, v220
	v_pk_mul_f32 v[52:53], v[166:167], v[166:167]
	s_nop 0
	v_add_f32_e32 v52, v52, v54
	v_add_f32_e32 v89, v53, v52
	ds_bpermute_b32 v168, v153, v89
	v_cndmask_b32_e32 v154, v218, v226, vcc
	v_lshlrev_b32_e32 v154, 2, v154
	v_mfma_f32_16x16x32_bf16 v[52:55], v[192:195], v[202:205], v[160:163]
	s_waitcnt lgkmcnt(0)
	v_add_f32_e32 v89, v89, v168
	s_nop 0
	ds_bpermute_b32 v160, v154, v89
	v_cvt_pk_bf16_f32 v162, v164, v165
	v_cvt_pk_bf16_f32 v163, v166, v167
	global_store_dwordx2 v[92:93], v[162:163], off
	s_and_saveexec_b64 s[0:1], s[58:59]
	s_cbranch_execz .LBB0_362
	s_waitcnt lgkmcnt(0)
	v_add_f32_e32 v89, v89, v160
	ds_write_b32 v114, v89

.Lscan2_skip:
	s_mul_hi_i32 s1, s20, 0x3400
	s_mulk_i32 s20, 0x3400
	s_add_u32 s0, s96, s20
	s_addc_u32 s1, s97, s1
	v_readlane_b32 s2, v254, 36
	v_lshl_add_u64 v[32:33], s[0:1], 0, v[2:3]
	v_add_u32_e32 v54, v115, v96
	v_mov_b32_e32 v2, s2
	ds_read_b32 v2, v2
	ds_write_b64 v54, v[66:67]
	v_add_u32_e32 v54, v115, v97
	ds_write_b64 v54, v[68:69]
	ds_read_b64 v[54:55], v117
	ds_read_b64 v[162:163], v116
	v_lshlrev_b32_e32 v161, 16, v68
	v_lshlrev_b32_e32 v160, 16, v66
	v_lshl_add_u64 v[16:17], v[72:73], 1, v[32:33]
	s_waitcnt lgkmcnt(1)
	v_sub_f32_e32 v54, v2, v54
	v_sub_f32_e32 v55, v2, v55
	v_mul_f32_e32 v54, 0x3fb8aa3b, v54
	v_mul_f32_e32 v55, 0x3fb8aa3b, v55
	v_exp_f32_e32 v54, v54
	v_exp_f32_e32 v55, v55
	s_waitcnt lgkmcnt(0)
	v_pk_mul_f32 v[164:165], v[162:163], v[160:161]
	v_lshl_add_u64 v[24:25], v[74:75], 1, v[32:33]
	v_cvt_pk_bf16_f32 v89, v164, v165
	v_pk_mul_f32 v[54:55], v[162:163], v[54:55]
	v_lshl_add_u64 v[28:29], v[76:77], 1, v[32:33]
	v_pk_mul_f32 v[160:161], v[54:55], v[160:161]
	v_lshl_add_u64 v[32:33], v[78:79], 1, v[32:33]
	v_cvt_pk_bf16_f32 v155, v160, v161
	v_and_b32_e32 v161, 0xffff0000, v68
	v_and_b32_e32 v160, 0xffff0000, v66
	v_pk_mul_f32 v[164:165], v[162:163], v[160:161]
	v_pk_mul_f32 v[160:161], v[54:55], v[160:161]
	v_cvt_pk_bf16_f32 v66, v164, v165
	ds_write2_b32 v130, v89, v66 offset1:36
	v_cvt_pk_bf16_f32 v66, v160, v161
	v_lshlrev_b32_e32 v161, 16, v69
	v_lshlrev_b32_e32 v160, 16, v67
	v_and_b32_e32 v69, 0xffff0000, v69
	v_and_b32_e32 v68, 0xffff0000, v67
	ds_write2_b32 v137, v155, v66 offset1:36
	v_pk_mul_f32 v[164:165], v[162:163], v[160:161]
	v_pk_mul_f32 v[66:67], v[162:163], v[68:69]
	v_cvt_pk_bf16_f32 v89, v164, v165
	v_pk_mul_f32 v[160:161], v[54:55], v[160:161]
	v_cvt_pk_bf16_f32 v66, v66, v67
	v_pk_mul_f32 v[54:55], v[54:55], v[68:69]
	v_cvt_pk_bf16_f32 v155, v160, v161
	ds_write2_b32 v130, v89, v66 offset0:72 offset1:108
	v_cvt_pk_bf16_f32 v54, v54, v55
	v_mov_b32_e32 v89, v3
	ds_write2_b32 v137, v155, v54 offset0:72 offset1:108
	v_lshl_add_u64 v[54:55], s[0:1], 0, v[88:89]
	v_lshl_add_u64 v[66:67], v[80:81], 1, v[54:55]
	v_lshl_add_u64 v[54:55], v[82:83], 1, v[54:55]
	global_load_dwordx4 v[16:19], v[16:17], off
	v_add_u32_e32 v155, s36, v123
	global_load_dwordx4 v[24:27], v[24:25], off
	v_cmp_lt_i32_e32 vcc, -1, v155
	global_load_dwordx4 v[28:31], v[28:29], off
	s_and_b64 s[0:1], s[40:41], vcc
	global_load_dwordx4 v[32:35], v[32:33], off
	v_cmp_lt_u32_e32 vcc, 15, v155
	global_load_dwordx2 v[66:67], v[66:67], off
	s_or_b64 s[20:21], s[64:65], vcc
	global_load_dwordx2 v[68:69], v[54:55], off
	s_waitcnt lgkmcnt(0)
	s_barrier
	s_cmp_eq_u64 s[82:83], 0
	s_cbranch_scc1 .Lssq2_own
	v_lshlrev_b32_e32 v201, 2, v232
	global_store_dword v201, v3, s[66:67]
	s_cmp_eq_u32 s99, 0
	s_cbranch_scc1 .LBB0_373
	v_mul_f32_e32 v2, 0x3fb8aa3b, v2
	v_exp_f32_e32 v2, v2
	ds_read_b128 v[176:179], v139
	ds_read_b64_tr_b16 v[180:181], v140
	ds_read_b64_tr_b16 v[182:183], v140 offset:1088
	ds_read_b64_tr_b16 v[184:185], v140 offset:32
	ds_read_b64_tr_b16 v[186:187], v140 offset:1120
	ds_read_b64_tr_b16 v[188:189], v140 offset:64
	ds_read_b64_tr_b16 v[190:191], v140 offset:1152
	ds_read_b64_tr_b16 v[192:193], v140 offset:96
	ds_read_b64_tr_b16 v[194:195], v140 offset:1184
	ds_read_b128 v[172:175], v159
	ds_read_b64_tr_b16 v[160:161], v140 offset:8704
	ds_read_b64_tr_b16 v[162:163], v140 offset:9792
	ds_read_b64_tr_b16 v[164:165], v140 offset:8736
	ds_read_b64_tr_b16 v[166:167], v140 offset:9824
	v_pk_mul_f32 v[50:51], v[50:51], v[2:3] op_sel_hi:[1,0]
	v_pk_mul_f32 v[48:49], v[48:49], v[2:3] op_sel_hi:[1,0]
	v_pk_mul_f32 v[42:43], v[42:43], v[2:3] op_sel_hi:[1,0]
	v_pk_mul_f32 v[40:41], v[40:41], v[2:3] op_sel_hi:[1,0]
	v_pk_mul_f32 v[46:47], v[46:47], v[2:3] op_sel_hi:[1,0]
	v_pk_mul_f32 v[44:45], v[44:45], v[2:3] op_sel_hi:[1,0]
	v_pk_mul_f32 v[38:39], v[38:39], v[2:3] op_sel_hi:[1,0]
	v_pk_mul_f32 v[36:37], v[36:37], v[2:3] op_sel_hi:[1,0]
	s_waitcnt lgkmcnt(5)
	v_mfma_f32_16x16x32_bf16 v[48:51], v[180:183], v[176:179], v[48:51]
	v_mfma_f32_16x16x32_bf16 v[40:43], v[184:187], v[176:179], v[40:43]
	v_mfma_f32_16x16x32_bf16 v[44:47], v[188:191], v[176:179], v[44:47]
	v_mfma_f32_16x16x32_bf16 v[36:39], v[192:195], v[176:179], v[36:39]
	ds_read_b64_tr_b16 v[168:169], v140 offset:8768
	ds_read_b64_tr_b16 v[170:171], v140 offset:9856
	ds_read_b64_tr_b16 v[202:203], v140 offset:8800
	ds_read_b64_tr_b16 v[204:205], v140 offset:9888
	s_waitcnt lgkmcnt(4)
	v_mfma_f32_16x16x32_bf16 v[48:51], v[160:163], v[172:175], v[48:51]
	v_mfma_f32_16x16x32_bf16 v[40:43], v[164:167], v[172:175], v[40:43]
	s_waitcnt lgkmcnt(0)
	v_mfma_f32_16x16x32_bf16 v[44:47], v[168:171], v[172:175], v[44:47]
	v_mfma_f32_16x16x32_bf16 v[36:39], v[202:205], v[172:175], v[36:39]
	ds_read_b128 v[160:163], v156 offset:34816
	ds_read_b128 v[164:167], v156 offset:34880
	ds_read_b128 v[168:171], v156 offset:17408
	ds_read_b128 v[172:175], v156 offset:17472
	ds_read_b128 v[176:179], v138
	ds_read_b128 v[180:183], v138 offset:64
	ds_read_b128 v[184:187], v138 offset:4352
	ds_read_b128 v[188:191], v138 offset:4416
	ds_read_b128 v[192:195], v156 offset:34944
	ds_read_b128 v[202:205], v156 offset:35008
	ds_read_b128 v[206:209], v156 offset:17536
	ds_read_b128 v[210:213], v156 offset:17600
	ds_read_b128 v[214:217], v138 offset:128
	ds_read_b128 v[236:239], v138 offset:192
	ds_read_b128 v[240:243], v138 offset:4480
	ds_read_b128 v[244:247], v138 offset:4544
	s_waitcnt lgkmcnt(11)
	v_mfma_f32_16x16x32_bf16 v[248:251], v[160:163], v[176:179], 0
	v_mfma_f32_16x16x32_bf16 v[176:179], v[168:171], v[176:179], 0
	s_waitcnt lgkmcnt(9)
	v_mfma_f32_16x16x32_bf16 v[160:163], v[160:163], v[184:187], 0
	v_mfma_f32_16x16x32_bf16 v[168:171], v[168:171], v[184:187], 0
	v_mfma_f32_16x16x32_bf16 v[184:187], v[164:167], v[180:183], v[248:251]
	v_mfma_f32_16x16x32_bf16 v[176:179], v[172:175], v[180:183], v[176:179]
	s_waitcnt lgkmcnt(8)
	v_mfma_f32_16x16x32_bf16 v[160:163], v[164:167], v[188:191], v[160:163]
	v_mfma_f32_16x16x32_bf16 v[164:167], v[172:175], v[188:191], v[168:171]
	s_waitcnt lgkmcnt(3)
	v_mfma_f32_16x16x32_bf16 v[168:171], v[192:195], v[214:217], v[184:187]
	v_mfma_f32_16x16x32_bf16 v[172:175], v[206:209], v[214:217], v[176:179]
	s_waitcnt lgkmcnt(1)
	v_mfma_f32_16x16x32_bf16 v[160:163], v[192:195], v[240:243], v[160:163]
	s_nop 0
	v_mfma_f32_16x16x32_bf16 v[164:167], v[206:209], v[240:243], v[164:167]
	v_mfma_f32_16x16x32_bf16 v[168:171], v[202:205], v[236:239], v[168:171]
	v_mfma_f32_16x16x32_bf16 v[172:175], v[210:213], v[236:239], v[172:175]
	s_waitcnt lgkmcnt(0)
	v_mfma_f32_16x16x32_bf16 v[160:163], v[202:205], v[244:247], v[160:163]
	v_mfma_f32_16x16x32_bf16 v[164:167], v[210:213], v[244:247], v[164:167]
	ds_read_b32 v88, v120
	ds_read_b128 v[202:205], v131
	s_waitcnt lgkmcnt(0)
	v_pk_add_f32 v[198:199], v[88:89], v[202:203] op_sel:[0,0] op_sel_hi:[0,1] neg_lo:[0,1] neg_hi:[0,1]
	v_pk_add_f32 v[222:223], v[88:89], v[204:205] op_sel:[0,0] op_sel_hi:[0,1] neg_lo:[0,1] neg_hi:[0,1]
	v_pk_mul_f32 v[198:199], v[198:199], s[100:101]
	v_pk_mul_f32 v[222:223], v[222:223], s[100:101]
	v_exp_f32_e32 v198, v198
	v_exp_f32_e32 v199, v199
	v_exp_f32_e32 v222, v222
	v_exp_f32_e32 v223, v223
	v_pk_mul_f32 v[198:199], v[172:173], v[198:199]
	v_pk_mul_f32 v[222:223], v[174:175], v[222:223]
	v_cndmask_b32_e64 v198, v198, 0, s[42:43]
	v_cndmask_b32_e64 v199, 0, v199, s[44:45]
	v_cndmask_b32_e64 v222, v222, 0, s[46:47]
	v_cndmask_b32_e64 v223, v223, 0, s[48:49]
	v_cvt_pk_bf16_f32 v54, v198, v199
	v_cvt_pk_bf16_f32 v55, v222, v223
	ds_write_b64 v144, v[54:55]
	ds_read_b32 v55, v121
	ds_read_b128 v[172:175], v131
	v_mul_f32_e32 v54, 0x3fb8aa3b, v88
	v_exp_f32_e32 v54, v54
	s_waitcnt lgkmcnt(0)
	v_mul_f32_e32 v88, 0x3fb8aa3b, v55
	v_pk_add_f32 v[198:199], v[54:55], v[172:173] op_sel:[1,0] op_sel_hi:[1,1] neg_lo:[0,1] neg_hi:[0,1]
	v_pk_add_f32 v[222:223], v[54:55], v[174:175] op_sel:[1,0] op_sel_hi:[1,1] neg_lo:[0,1] neg_hi:[0,1]
	v_pk_mul_f32 v[198:199], v[198:199], s[100:101]
	v_pk_mul_f32 v[222:223], v[222:223], s[100:101]
	v_exp_f32_e32 v198, v198
	v_exp_f32_e32 v199, v199
	v_exp_f32_e32 v222, v222
	v_exp_f32_e32 v223, v223
	v_exp_f32_e32 v88, v88
	v_pk_mul_f32 v[198:199], v[164:165], v[198:199]
	v_pk_mul_f32 v[222:223], v[166:167], v[222:223]
	v_cndmask_b32_e64 v198, v198, 0, s[50:51]
	v_cndmask_b32_e64 v199, 0, v199, s[52:53]
	v_cndmask_b32_e64 v222, v222, 0, s[54:55]
	v_cndmask_b32_e64 v223, v223, 0, s[56:57]
	v_cvt_pk_bf16_f32 v164, v198, v199
	v_cvt_pk_bf16_f32 v165, v222, v223
	ds_write_b64 v145, v[164:165]
	v_add_u32_e32 v55, v122, v111
	v_add_u32_e32 v2, v122, v113
	s_waitcnt lgkmcnt(0)
	s_barrier
	ds_read_b128 v[176:179], v2
	ds_read_b128 v[184:187], v55
	ds_read_b128 v[180:183], v150
	ds_read_b128 v[188:191], v150 offset:64
	ds_read_b128 v[192:195], v150 offset:2304
	ds_read_b128 v[202:205], v150 offset:2368
	s_branch .LsegB2_join

.LBB0_373:
	ds_read_b128 v[160:163], v156 offset:34816
	ds_read_b128 v[164:167], v156 offset:34880
	ds_read_b128 v[168:171], v156 offset:17408
	ds_read_b128 v[172:175], v156 offset:17472
	ds_read_b128 v[176:179], v138
	ds_read_b128 v[180:183], v138 offset:64
	ds_read_b128 v[184:187], v138 offset:4352
	ds_read_b128 v[188:191], v138 offset:4416
	ds_read_b128 v[192:195], v156 offset:34944
	ds_read_b128 v[202:205], v156 offset:35008
	ds_read_b128 v[206:209], v156 offset:17536
	ds_read_b128 v[210:213], v156 offset:17600
	ds_read_b128 v[214:217], v138 offset:128
	ds_read_b128 v[236:239], v138 offset:192
	ds_read_b128 v[240:243], v138 offset:4480
	ds_read_b128 v[244:247], v138 offset:4544
	s_waitcnt lgkmcnt(11)
	v_mfma_f32_16x16x32_bf16 v[248:251], v[160:163], v[176:179], 0
	v_mfma_f32_16x16x32_bf16 v[176:179], v[168:171], v[176:179], 0
	s_waitcnt lgkmcnt(9)
	v_mfma_f32_16x16x32_bf16 v[160:163], v[160:163], v[184:187], 0
	v_mfma_f32_16x16x32_bf16 v[168:171], v[168:171], v[184:187], 0
	v_mfma_f32_16x16x32_bf16 v[184:187], v[164:167], v[180:183], v[248:251]
	v_mfma_f32_16x16x32_bf16 v[176:179], v[172:175], v[180:183], v[176:179]
	s_waitcnt lgkmcnt(8)
	v_mfma_f32_16x16x32_bf16 v[160:163], v[164:167], v[188:191], v[160:163]
	v_mfma_f32_16x16x32_bf16 v[164:167], v[172:175], v[188:191], v[168:171]
	s_waitcnt lgkmcnt(3)
	v_mfma_f32_16x16x32_bf16 v[168:171], v[192:195], v[214:217], v[184:187]
	v_mfma_f32_16x16x32_bf16 v[172:175], v[206:209], v[214:217], v[176:179]
	s_waitcnt lgkmcnt(1)
	v_mfma_f32_16x16x32_bf16 v[160:163], v[192:195], v[240:243], v[160:163]
	s_nop 0
	ds_read_b128 v[176:179], v139
	ds_read_b64_tr_b16 v[180:181], v140
	ds_read_b64_tr_b16 v[182:183], v140 offset:1088
	ds_read_b64_tr_b16 v[184:185], v140 offset:32
	ds_read_b64_tr_b16 v[186:187], v140 offset:1120
	ds_read_b64_tr_b16 v[188:189], v140 offset:64
	ds_read_b64_tr_b16 v[190:191], v140 offset:1152
	ds_read_b64_tr_b16 v[192:193], v140 offset:96
	ds_read_b64_tr_b16 v[194:195], v140 offset:1184
	v_mfma_f32_16x16x32_bf16 v[164:167], v[206:209], v[240:243], v[164:167]
	v_mfma_f32_16x16x32_bf16 v[168:171], v[202:205], v[236:239], v[168:171]
	v_mfma_f32_16x16x32_bf16 v[172:175], v[210:213], v[236:239], v[172:175]
	s_waitcnt lgkmcnt(9)
	v_mfma_f32_16x16x32_bf16 v[160:163], v[202:205], v[244:247], v[160:163]
	v_mfma_f32_16x16x32_bf16 v[164:167], v[210:213], v[244:247], v[164:167]
	ds_read_b32 v88, v120
	ds_read_b128 v[202:205], v131
	s_waitcnt lgkmcnt(0)
	v_pk_add_f32 v[198:199], v[88:89], v[202:203] op_sel:[0,0] op_sel_hi:[0,1] neg_lo:[0,1] neg_hi:[0,1]
	v_pk_add_f32 v[222:223], v[88:89], v[204:205] op_sel:[0,0] op_sel_hi:[0,1] neg_lo:[0,1] neg_hi:[0,1]
	v_pk_mul_f32 v[198:199], v[198:199], s[100:101]
	v_pk_mul_f32 v[222:223], v[222:223], s[100:101]
	v_exp_f32_e32 v198, v198
	v_exp_f32_e32 v199, v199
	v_exp_f32_e32 v222, v222
	v_exp_f32_e32 v223, v223
	v_pk_mul_f32 v[198:199], v[172:173], v[198:199]
	v_pk_mul_f32 v[222:223], v[174:175], v[222:223]
	v_cndmask_b32_e64 v198, v198, 0, s[42:43]
	v_cndmask_b32_e64 v199, 0, v199, s[44:45]
	v_cndmask_b32_e64 v222, v222, 0, s[46:47]
	v_cndmask_b32_e64 v223, v223, 0, s[48:49]
	v_cvt_pk_bf16_f32 v54, v198, v199
	v_cvt_pk_bf16_f32 v55, v222, v223
	ds_write_b64 v144, v[54:55]
	ds_read_b32 v55, v121
	ds_read_b128 v[172:175], v131
	v_mul_f32_e32 v54, 0x3fb8aa3b, v88
	v_exp_f32_e32 v54, v54
	s_waitcnt lgkmcnt(0)
	v_mul_f32_e32 v88, 0x3fb8aa3b, v55
	v_pk_add_f32 v[198:199], v[54:55], v[172:173] op_sel:[1,0] op_sel_hi:[1,1] neg_lo:[0,1] neg_hi:[0,1]
	v_pk_add_f32 v[222:223], v[54:55], v[174:175] op_sel:[1,0] op_sel_hi:[1,1] neg_lo:[0,1] neg_hi:[0,1]
	v_pk_mul_f32 v[198:199], v[198:199], s[100:101]
	v_pk_mul_f32 v[222:223], v[222:223], s[100:101]
	v_exp_f32_e32 v198, v198
	v_exp_f32_e32 v199, v199
	v_exp_f32_e32 v222, v222
	v_exp_f32_e32 v223, v223
	v_exp_f32_e32 v88, v88
	v_pk_mul_f32 v[198:199], v[164:165], v[198:199]
	v_pk_mul_f32 v[222:223], v[166:167], v[222:223]
	v_cndmask_b32_e64 v198, v198, 0, s[50:51]
	v_cndmask_b32_e64 v199, 0, v199, s[52:53]
	v_cndmask_b32_e64 v222, v222, 0, s[54:55]
	v_cndmask_b32_e64 v223, v223, 0, s[56:57]
	v_cvt_pk_bf16_f32 v164, v198, v199
	v_cvt_pk_bf16_f32 v165, v222, v223
	ds_write_b64 v145, v[164:165]
	v_mul_f32_e32 v2, 0x3fb8aa3b, v2
	v_exp_f32_e32 v2, v2
	ds_read_b128 v[164:167], v159
	ds_read_b64_tr_b16 v[172:173], v140 offset:8704
	ds_read_b64_tr_b16 v[174:175], v140 offset:9792
	v_add_u32_e32 v55, v122, v111
	v_pk_mul_f32 v[50:51], v[50:51], v[2:3] op_sel_hi:[1,0]
	v_pk_mul_f32 v[48:49], v[48:49], v[2:3] op_sel_hi:[1,0]
	v_pk_mul_f32 v[42:43], v[42:43], v[2:3] op_sel_hi:[1,0]
	v_pk_mul_f32 v[40:41], v[40:41], v[2:3] op_sel_hi:[1,0]
	v_mfma_f32_16x16x32_bf16 v[48:51], v[180:183], v[176:179], v[48:51]
	v_mul_f32_e64 v46, v46, v2
	v_mul_f32_e64 v47, v47, v2
	v_pk_mul_f32 v[44:45], v[44:45], v[2:3] op_sel_hi:[1,0]
	v_pk_mul_f32 v[38:39], v[38:39], v[2:3] op_sel_hi:[1,0]
	v_pk_mul_f32 v[36:37], v[36:37], v[2:3] op_sel_hi:[1,0]
	v_mfma_f32_16x16x32_bf16 v[40:43], v[184:187], v[176:179], v[40:43]
	v_add_u32_e32 v2, v122, v113
	v_mfma_f32_16x16x32_bf16 v[44:47], v[188:191], v[176:179], v[44:47]
	v_mfma_f32_16x16x32_bf16 v[36:39], v[192:195], v[176:179], v[36:39]
	ds_read_b64_tr_b16 v[176:177], v140 offset:8736
	ds_read_b64_tr_b16 v[178:179], v140 offset:9824
	ds_read_b64_tr_b16 v[180:181], v140 offset:8768
	ds_read_b64_tr_b16 v[182:183], v140 offset:9856
	s_waitcnt lgkmcnt(4)
	v_mfma_f32_16x16x32_bf16 v[48:51], v[172:175], v[164:167], v[48:51]
	ds_read_b64_tr_b16 v[172:173], v140 offset:8800
	ds_read_b64_tr_b16 v[174:175], v140 offset:9888
	s_waitcnt lgkmcnt(0)
	s_barrier
	s_waitcnt lgkmcnt(2)
	v_mfma_f32_16x16x32_bf16 v[40:43], v[176:179], v[164:167], v[40:43]
	ds_read_b128 v[176:179], v2
	ds_read_b128 v[184:187], v55
	s_waitcnt lgkmcnt(3)
	v_mfma_f32_16x16x32_bf16 v[44:47], v[180:183], v[164:167], v[44:47]
	ds_read_b128 v[180:183], v150
	ds_read_b128 v[188:191], v150 offset:64
	ds_read_b128 v[192:195], v150 offset:2304
	ds_read_b128 v[202:205], v150 offset:2368
	s_waitcnt lgkmcnt(6)
	v_mfma_f32_16x16x32_bf16 v[36:39], v[172:175], v[164:167], v[36:39]
.LsegB2_join:
	v_mul_f32_e64 v166, v170, v54
	v_mul_f32_e64 v167, v171, v54
	v_pk_mul_f32 v[164:165], v[168:169], v[54:55] op_sel_hi:[1,0]
	v_pk_mul_f32 v[162:163], v[162:163], v[88:89] op_sel_hi:[1,0]
	v_pk_mul_f32 v[160:161], v[160:161], v[88:89] op_sel_hi:[1,0]
	v_cvt_pk_bf16_f32 v54, v48, v49
	v_cvt_pk_bf16_f32 v55, v50, v51
	v_cvt_pk_bf16_f32 v88, v40, v41
	v_cvt_pk_bf16_f32 v89, v42, v43
	ds_write2_b64 v157, v[54:55], v[88:89] offset1:4
	v_cvt_pk_bf16_f32 v54, v44, v45
	v_cvt_pk_bf16_f32 v55, v46, v47
	v_cvt_pk_bf16_f32 v88, v36, v37
	v_cvt_pk_bf16_f32 v89, v38, v39
	ds_write2_b64 v157, v[54:55], v[88:89] offset0:8 offset1:12
	s_waitcnt vmcnt(9)
	v_lshlrev_b32_e32 v54, 16, v52
	v_and_b32_e32 v55, 0xffff0000, v52
	v_mul_f32_e32 v2, 0xbfb8aa3b, v54
	v_exp_f32_e32 v2, v2
	v_mul_f32_e32 v52, 0xbfb8aa3b, v55
	v_exp_f32_e32 v52, v52
	s_waitcnt lgkmcnt(5)
	v_mfma_f32_16x16x32_bf16 v[164:167], v[176:179], v[180:183], v[164:167]
	ds_read_b64 v[88:89], v132
	v_add_f32_e32 v2, 1.0, v2
	v_rcp_f32_e32 v156, v2
	v_add_f32_e32 v2, 1.0, v52
	s_waitcnt lgkmcnt(4)
	v_mfma_f32_16x16x32_bf16 v[158:161], v[176:179], v[192:195], v[160:163]
	v_rcp_f32_e32 v157, v2
	v_lshlrev_b32_e32 v52, 16, v53
	v_and_b32_e32 v53, 0xffff0000, v53
	v_mfma_f32_16x16x32_bf16 v[162:165], v[184:187], v[188:191], v[164:167]
	v_mul_f32_e64 v54, v156, v54
	v_mul_f32_e64 v55, v157, v55
	v_mul_f32_e32 v2, 0xbfb8aa3b, v52
	v_exp_f32_e32 v2, v2
	s_waitcnt lgkmcnt(0)
	v_lshlrev_b32_e32 v166, 16, v88
	v_and_b32_e32 v167, 0xffff0000, v88
	s_nop 0
	v_pk_fma_f32 v[162:163], v[0:1], v[166:167], v[162:163]
	v_add_f32_e32 v2, 1.0, v2
	v_pk_mul_f32 v[156:157], v[54:55], v[162:163]
	v_mul_f32_e32 v54, 0xbfb8aa3b, v53
	v_exp_f32_e32 v88, v54
	v_rcp_f32_e32 v162, v2
	v_pk_mul_f32 v[54:55], v[156:157], v[156:157]
	v_cvt_pk_bf16_f32 v156, v156, v157
	v_add_f32_e32 v2, 1.0, v88
	v_rcp_f32_e32 v163, v2
	v_lshlrev_b32_e32 v88, 16, v89
	v_and_b32_e32 v89, 0xffff0000, v89
	v_pk_fma_f32 v[88:89], v[0:1], v[88:89], v[164:165]
	v_pk_mul_f32 v[52:53], v[162:163], v[52:53]
	v_add_f32_e32 v2, v54, v55
	v_pk_mul_f32 v[162:163], v[52:53], v[88:89]
	v_lshl_add_u64 v[92:93], v[86:87], 0, v[92:93]
	v_pk_mul_f32 v[52:53], v[162:163], v[162:163]
	v_cvt_pk_bf16_f32 v157, v162, v163
	v_add_f32_e32 v2, v52, v2
	v_add_f32_e32 v2, v53, v2
	ds_bpermute_b32 v88, v153, v2
	v_mfma_f32_16x16x32_bf16 v[52:55], v[184:187], v[202:205], v[158:161]
	global_store_dwordx2 v[92:93], v[156:157], off
	s_waitcnt lgkmcnt(0)
	v_add_f32_e32 v2, v2, v88
	ds_bpermute_b32 v88, v154, v2
	s_and_saveexec_b64 s[0:1], s[58:59]
	s_cbranch_execz .LBB0_375
	s_waitcnt lgkmcnt(0)
	v_add_f32_e32 v2, v2, v88
	ds_write_b32 v114, v2
